# P5 work queue: static first ticket per workgroup (no-op tickets skipped), shared counter serves tickets 480.. ; on top of two-level publishes
# speedup vs baseline: 1.0046x; 1.0046x over previous
; #define LAS __attribute__((address_space(3)))
; #define PH_BEGIN const int tid = otid(); const int G = gridDim.x; const int bid = osi((int)blockIdx.x); unsigned char* ws = osp(P.ws); float* out = osp(P.out); unsigned char* U = ws + WS_U; (void)tid; (void)G; (void)bid; (void)out; (void)U;
; __global__ void __launch_bounds__(512, 2) mega(Params P) {
;     ...
;         {
;             LAS int* sitem = (LAS int*)(lds + LDS_MISC);
;     ...
;             for (int rep = 0; rep < REP_P5; ++rep)
;             for (;;) {
;                 PH_BEGIN
;                 __syncthreads();
;                 if (tid == 0) *sitem = (int)atomicAdd(WSP(unsigned, WS_CTL) + 3600 + l + 2 * rep, 1u);
;                 __syncthreads();
;                 const int it = *sitem;
.LBB0_886:
	s_or_b64 exec, exec, s[0:1]
	s_lshl_b32 s0, s96, 3
	s_lshl_b32 s92, s96, 8
	v_readlane_b32 s72, v253, 0
	s_lshl_b32 s54, s96, 10
	s_lshl_b32 s36, s96, 14
	s_lshl_b32 s31, s96, 4
	v_writelane_b32 v254, s0, 38
	s_lshl_b64 s[0:1], s[92:93], 2
	v_readlane_b32 s86, v253, 14
	v_readlane_b32 s87, v253, 15
	s_add_u32 s37, s86, s0
	s_mov_b32 s0, s96
	s_addc_u32 s38, s87, s1
	v_writelane_b32 v254, s0, 56
	s_mov_b32 s2, s96
	s_mov_b32 s3, s93
	v_writelane_b32 v254, s1, 57
	s_lshl_b64 s[34:35], s[2:3], 2
	v_writelane_b32 v254, s31, 46
	s_waitcnt lgkmcnt(0)
	s_barrier
	v_readlane_b32 s73, v253, 1
	v_readlane_b32 s74, v253, 2
	v_readlane_b32 s75, v253, 3
	v_readlane_b32 s76, v253, 4
	v_readlane_b32 s77, v253, 5
	v_readlane_b32 s78, v253, 6
	v_readlane_b32 s79, v253, 7
	v_readlane_b32 s80, v253, 8
	v_readlane_b32 s81, v253, 9
	v_readlane_b32 s82, v253, 10
	v_readlane_b32 s83, v253, 11
	v_readlane_b32 s84, v253, 12
	v_readlane_b32 s85, v253, 13
	s_mov_b32 s98, 1
	s_branch .LBB0_889

; #define PH_BEGIN const int tid = otid(); const int G = gridDim.x; const int bid = osi((int)blockIdx.x); unsigned char* ws = osp(P.ws); float* out = osp(P.out); unsigned char* U = ws + WS_U; (void)tid; (void)G; (void)bid; (void)out; (void)U;
; __global__ void __launch_bounds__(512, 2) mega(Params P) {
;     ...
;             for (;;) {
;                 PH_BEGIN
;                 __syncthreads();
;                 if (tid == 0) *sitem = (int)atomicAdd(WSP(unsigned, WS_CTL) + 3600 + l + 2 * rep, 1u);
;                 __syncthreads();
;                 const int it = *sitem;
;                 if (it >= 1280) break;
;                 int type, b, hh, qb = 0, samp = 0, grp = 0;
;     ...
;                 if (it < 256) { type = 0; grp = 7 - (it >> 5); b = (it >> 2) & 7; hh = it & 3; }
;     ...
;                 if (it < 256) { if (it >= 32) continue; type = 0; grp = 7; b = (it >> 2) & 7; hh = it & 3; }
.LBB0_889:
	s_mov_b32 s0, s21
	v_mbcnt_lo_u32_b32 v0, -1, 0
	v_mbcnt_hi_u32_b32 v0, -1, v0
	s_nop 0
	v_lshl_add_u32 v148, s0, 6, v0
	s_mov_b32 s0, s97
	v_cmp_eq_u32_e32 vcc, 0, v148
	v_readlane_b32 s0, v254, 19
	v_readlane_b32 s4, v254, 23
	v_readlane_b32 s5, v254, 24
	v_readlane_b32 s6, v254, 25
	v_readlane_b32 s7, v254, 26
	v_readlane_b32 s1, v254, 20
	s_mov_b64 s[52:53], s[6:7]
	s_mov_b64 s[16:17], s[4:5]
	v_readlane_b32 s2, v254, 21
	v_readlane_b32 s3, v254, 22
	s_barrier
	s_and_saveexec_b64 s[0:1], vcc
	s_cbranch_execz .LBB0_893
	s_cmp_eq_u32 s98, 0
	s_cbranch_scc1 .Ldq_dyn
	s_mov_b32 s98, 0
	s_add_i32 s2, s97, 0xe0
	s_cmp_lt_u32 s97, 32
	s_cselect_b32 s2, s97, s2
	s_branch .Ldq_pub
.Ldq_dyn:
	s_add_u32 s6, s52, s34
	s_addc_u32 s7, s53, s35
	v_mov_b32_e32 v1, 1
	v_mov_b32_e32 v2, 0x3000
	global_atomic_add v1, v2, v1, s[6:7] offset:2112 sc0
	s_waitcnt vmcnt(0)
	v_readfirstlane_b32 s2, v1
	s_addk_i32 s2, 0x1e0
.Ldq_pub:
	v_mov_b32_e32 v1, s89
	v_mov_b32_e32 v0, s2
	ds_write_b32 v1, v0

; __global__ void __launch_bounds__(512, 2) mega(Params P) {
	.amdhsa_kernel _Z4mega6Params
		.amdhsa_group_segment_fixed_size 0
		.amdhsa_private_segment_fixed_size 0
		.amdhsa_kernarg_size 480
		.amdhsa_user_sgpr_count 2
		.amdhsa_user_sgpr_dispatch_ptr 0
		.amdhsa_user_sgpr_queue_ptr 0
		.amdhsa_user_sgpr_kernarg_segment_ptr 1
		.amdhsa_user_sgpr_dispatch_id 0
		.amdhsa_user_sgpr_kernarg_preload_length 0
		.amdhsa_user_sgpr_kernarg_preload_offset 0
		.amdhsa_user_sgpr_private_segment_size 0
		.amdhsa_uses_dynamic_stack 0
		.amdhsa_enable_private_segment 0
		.amdhsa_system_sgpr_workgroup_id_x 1
		.amdhsa_system_sgpr_workgroup_id_y 0
		.amdhsa_system_sgpr_workgroup_id_z 0
		.amdhsa_system_sgpr_workgroup_info 0
		.amdhsa_system_vgpr_workitem_id 2
		.amdhsa_next_free_vgpr 256
		.amdhsa_next_free_sgpr 102
		.amdhsa_accum_offset 256
		.amdhsa_reserve_vcc 1
		.amdhsa_float_round_mode_32 0
		.amdhsa_float_round_mode_16_64 0
		.amdhsa_float_denorm_mode_32 3
		.amdhsa_float_denorm_mode_16_64 3
		.amdhsa_dx10_clamp 1
		.amdhsa_ieee_mode 1
		.amdhsa_fp16_overflow 0
		.amdhsa_tg_split 0
		.amdhsa_exception_fp_ieee_invalid_op 0
		.amdhsa_exception_fp_denorm_src 0
		.amdhsa_exception_fp_ieee_div_zero 0
		.amdhsa_exception_fp_ieee_overflow 0
		.amdhsa_exception_fp_ieee_underflow 0
		.amdhsa_exception_fp_ieee_inexact 0
		.amdhsa_exception_int_div_zero 0
	.end_amdhsa_kernel

; __global__ void __launch_bounds__(512, 2) mega(Params P) {
amdhsa.kernels:
  - .agpr_count:     0
    .args:
      - .offset:         0
        .size:           224
        .value_kind:     by_value
      - .offset:         224
        .size:           4
        .value_kind:     hidden_block_count_x
      - .offset:         228
        .size:           4
        .value_kind:     hidden_block_count_y
      - .offset:         232
        .size:           4
        .value_kind:     hidden_block_count_z
      - .offset:         236
        .size:           2
        .value_kind:     hidden_group_size_x
      - .offset:         238
        .size:           2
        .value_kind:     hidden_group_size_y
      - .offset:         240
        .size:           2
        .value_kind:     hidden_group_size_z
      - .offset:         242
        .size:           2
        .value_kind:     hidden_remainder_x
      - .offset:         244
        .size:           2
        .value_kind:     hidden_remainder_y
      - .offset:         246
        .size:           2
        .value_kind:     hidden_remainder_z
      - .offset:         264
        .size:           8
        .value_kind:     hidden_global_offset_x
      - .offset:         272
        .size:           8
        .value_kind:     hidden_global_offset_y
      - .offset:         280
        .size:           8
        .value_kind:     hidden_global_offset_z
      - .offset:         288
        .size:           2
        .value_kind:     hidden_grid_dims
      - .offset:         312
        .size:           8
        .value_kind:     hidden_multigrid_sync_arg
      - .offset:         344
        .size:           4
        .value_kind:     hidden_dynamic_lds_size
    .group_segment_fixed_size: 0
    .kernarg_segment_align: 8
    .kernarg_segment_size: 480
    .language:       OpenCL C
    .language_version:
      - 2
      - 0
    .max_flat_workgroup_size: 512
    .name:           _Z4mega6Params
    .private_segment_fixed_size: 0
    .sgpr_count:     108
    .sgpr_spill_count: 236
    .symbol:         _Z4mega6Params.kd
    .uniform_work_group_size: 1
    .uses_dynamic_stack: false
    .vgpr_count:     256
    .vgpr_spill_count: 0
    .wavefront_size: 64
